# v6 + one static s_setprio 1 for waves 4-7 for the whole attention phase
# baseline (speedup 1.0000x reference)
; __global__ void __launch_bounds__(NTHR, 2) hybrid_fwd(Args args) {
;     ...
;     if (IN(11)) { BODY14; if (PROBE_ID == 2) { BODY14; } if (hi > 13) xcd_barrier(bar); }
.LBB0_1054:
	s_cmp_lt_i32 s80, 12
	s_cselect_b64 s[0:1], -1, 0
	s_cmp_gt_i32 s81, 11
	s_cselect_b64 s[2:3], -1, 0
	s_and_b64 s[0:1], s[0:1], s[2:3]
	s_andn2_b64 vcc, exec, s[0:1]
	s_cbranch_vccnz .LBB0_1446
	v_readfirstlane_b32 s98, v0
	s_lshr_b32 s98, s98, 8
	s_cmp_eq_u32 s98, 1
	s_cbranch_scc0 .Lap_skip
	s_setprio 1
.Lap_skip:
	s_and_b32 s0, s82, 7
	s_cmp_lg_u32 s0, 0
	s_mov_b32 s50, s96
	s_cbranch_scc1 .LBB0_1057
	s_ashr_i32 s1, s96, 31
	s_lshr_b32 s1, s1, 29
	s_add_i32 s1, s96, s1
	s_and_b32 s2, s1, -8
	s_ashr_i32 s0, s82, 3
	s_sub_i32 s2, s96, s2
	s_mul_i32 s0, s0, s2
	s_ashr_i32 s1, s1, 3
	s_add_i32 s50, s0, s1

; #define SEAM(k) do { if (IN((k) + 1)) grid.sync(); } while (0)
; #define GEMM_STD(Aptr, Bptr, ldk, Ncols, EpiT, Eobj) do { pg8::Gemm g_{(const bf16*)(Aptr), (const bf16*)(Bptr), (ldk), (ldk), (ldk), 0, 0}; pg8::StaticOrder S_; S_.init(M, (Ncols), (int)gridDim.x, (int)blockIdx.x); \
;         pg8::gemm_phase<EpiT, pg8::StaticOrder, true, true>((LAS unsigned char*)lds, g_, S_, Eobj); } while (0)
; #define SEAM(k) do { if (hi > (k) + 1) { if (lo > hi) grid.sync(); xcd_barrier(bar); } } while (0)
; __global__ void __launch_bounds__(NTHR, 2) hybrid_fwd(Args args) {
;     ...
;     if (IN(11)) { BODY14; if (PROBE_ID == 2) { BODY14; } if (hi > 13) xcd_barrier(bar); }
;     if (IN(13)) { EpiRes<false> E{WSB(WS_MIX), WSB(WS_MIX), SSQ(4)}; GEMM_STD(WSB(WS_PP), WSB(WS_WO), 1024, 1024, EpiRes<false>, E); SEAM(13); }
.LBB0_1446:
	s_setprio 0
	s_cmp_lt_i32 s80, 14
	s_cselect_b64 s[0:1], -1, 0
	s_cmp_gt_i32 s81, 13
	s_cselect_b64 s[2:3], -1, 0
	s_and_b64 s[0:1], s[0:1], s[2:3]
	s_andn2_b64 vcc, exec, s[0:1]
	s_cbranch_vccnz .LBB0_1543
	v_mov_b32_e32 v10, v0
	s_cmpk_lt_i32 s96, 0x200
	s_cselect_b64 s[6:7], -1, 0
	s_cmpk_gt_i32 s96, 0x1ff
	v_readfirstlane_b32 s8, v10
	s_cbranch_scc0 .LBB0_1450
	s_andn2_b64 vcc, exec, s[6:7]
	s_cbranch_vccz .LBB0_1455
